# k10 + diff combine/sub-LN row loop rewritten as a rolled 2x4-row software-pipelined loop (loads one group ahead, DPP+readlane reduction, saddr addressing)
# speedup vs baseline: 1.0093x; 1.0048x over previous
.LBB0_410:
	s_add_u32 s96, s54, 0x13000000
	s_addc_u32 s97, s55, 0
	s_add_u32 s98, s54, 0x39300000
	s_addc_u32 s99, s55, 0
	s_mov_b32 s56, 0
	s_add_u32 s4, s96, 0x1000
	s_addc_u32 s5, s97, 0
	s_add_u32 s6, s98, 0x1000
	s_addc_u32 s7, s99, 0
	global_load_dwordx2 v[40:41], v184, s[4:5] offset:-4096
	global_load_dwordx2 v[42:43], v184, s[6:7] offset:-4096
	global_load_dwordx2 v[44:45], v184, s[4:5]
	global_load_dwordx2 v[46:47], v184, s[6:7]
	s_add_u32 s4, s4, 0x2000
	s_addc_u32 s5, s5, 0
	s_add_u32 s6, s6, 0x2000
	s_addc_u32 s7, s7, 0
	global_load_dwordx2 v[48:49], v184, s[4:5] offset:-4096
	global_load_dwordx2 v[50:51], v184, s[6:7] offset:-4096
	global_load_dwordx2 v[52:53], v184, s[4:5]
	global_load_dwordx2 v[54:55], v184, s[6:7]
.Lcmb_loop:
	s_add_u32 s4, s96, 0x5000
	s_addc_u32 s5, s97, 0
	s_add_u32 s6, s98, 0x5000
	s_addc_u32 s7, s99, 0
	global_load_dwordx2 v[56:57], v184, s[4:5] offset:-4096
	global_load_dwordx2 v[58:59], v184, s[6:7] offset:-4096
	global_load_dwordx2 v[60:61], v184, s[4:5]
	global_load_dwordx2 v[62:63], v184, s[6:7]
	s_add_u32 s4, s4, 0x2000
	s_addc_u32 s5, s5, 0
	s_add_u32 s6, s6, 0x2000
	s_addc_u32 s7, s7, 0
	global_load_dwordx2 v[64:65], v184, s[4:5] offset:-4096
	global_load_dwordx2 v[66:67], v184, s[6:7] offset:-4096
	global_load_dwordx2 v[68:69], v184, s[4:5]
	global_load_dwordx2 v[70:71], v184, s[6:7]
	s_waitcnt vmcnt(8)
	v_lshlrev_b32_e32 v8, 16, v40
	v_lshlrev_b32_e32 v19, 16, v42
	v_and_b32_e32 v29, 0xffff0000, v40
	v_and_b32_e32 v34, 0xffff0000, v42
	v_fma_f32 v20, -v18, v19, v8
	v_fma_f32 v21, -v18, v34, v29
	v_lshlrev_b32_e32 v8, 16, v41
	v_lshlrev_b32_e32 v19, 16, v43
	v_and_b32_e32 v29, 0xffff0000, v41
	v_and_b32_e32 v34, 0xffff0000, v43
	v_fma_f32 v30, -v18, v19, v8
	v_fma_f32 v31, -v18, v34, v29
	v_mul_f32_e32 v8, v21, v21
	v_mul_f32_e32 v19, v31, v31
	v_fmac_f32_e32 v8, v20, v20
	v_fmac_f32_e32 v19, v30, v30
	v_add_f32_e32 v8, v8, v19
	s_nop 1
	v_add_f32_dpp v8, v8, v8 quad_perm:[1,0,3,2] row_mask:0xf bank_mask:0xf
	s_nop 1
	v_add_f32_dpp v8, v8, v8 quad_perm:[2,3,0,1] row_mask:0xf bank_mask:0xf
	s_nop 1
	v_add_f32_dpp v8, v8, v8 row_half_mirror row_mask:0xf bank_mask:0xf
	s_nop 1
	v_add_f32_dpp v8, v8, v8 row_mirror row_mask:0xf bank_mask:0xf
	s_nop 1
	v_readlane_b32 s14, v8, 0
	v_readlane_b32 s15, v8, 16
	v_readlane_b32 s24, v8, 32
	v_readlane_b32 s25, v8, 48
	s_nop 2
	v_mov_b32_e32 v19, s15
	v_mov_b32_e32 v29, s25
	v_add_f32_e32 v19, s14, v19
	v_add_f32_e32 v29, s24, v29
	v_add_f32_e32 v8, v19, v29
	v_fmamk_f32 v8, v8, 0x3b800000, v191
	v_mul_f32_e32 v19, 0x4f800000, v8
	v_cmp_gt_f32_e32 vcc, s76, v8
	s_nop 1
	v_cndmask_b32_e32 v8, v8, v19, vcc
	v_sqrt_f32_e32 v19, v8
	s_nop 0
	v_add_u32_e32 v29, -1, v19
	v_add_u32_e32 v34, 1, v19
	v_fma_f32 v35, -v29, v19, v8
	v_fma_f32 v36, -v34, v19, v8
	v_cmp_ge_f32_e64 s[14:15], 0, v35
	s_nop 1
	v_cndmask_b32_e64 v19, v19, v29, s[14:15]
	v_cmp_lt_f32_e64 s[14:15], 0, v36
	s_nop 1
	v_cndmask_b32_e64 v19, v19, v34, s[14:15]
	v_mul_f32_e32 v29, 0x37800000, v19
	v_cndmask_b32_e32 v19, v19, v29, vcc
	v_cmp_class_f32_e32 vcc, v8, v192
	s_nop 1
	v_cndmask_b32_e32 v8, v19, v8, vcc
	v_div_scale_f32 v19, s[14:15], v8, v8, 1.0
	v_rcp_f32_e32 v34, v19
	v_div_scale_f32 v29, vcc, 1.0, v8, 1.0
	v_fma_f32 v35, -v19, v34, 1.0
	v_fmac_f32_e32 v34, v35, v34
	v_mul_f32_e32 v35, v29, v34
	v_fma_f32 v36, -v19, v35, v29
	v_fmac_f32_e32 v35, v36, v34
	v_fma_f32 v19, -v19, v35, v29
	v_div_fmas_f32 v19, v19, v34, v35
	v_div_fixup_f32 v8, v19, v8, 1.0
	v_mul_f32_e32 v20, v20, v8
	v_mul_f32_e32 v21, v21, v8
	v_mul_f32_e32 v30, v30, v8
	v_mul_f32_e32 v31, v31, v8
	v_mul_f32_e32 v20, v4, v20
	v_mul_f32_e32 v21, v5, v21
	v_mul_f32_e32 v30, v2, v30
	v_mul_f32_e32 v31, v3, v31
	v_cvt_pk_bf16_f32 v32, v20, v21
	v_cvt_pk_bf16_f32 v33, v30, v31
	s_lshl_b32 s14, s56, 3
	s_add_i32 s14, s14, s50
	s_add_i32 s14, s14, 0
	s_and_b32 s14, s14, 0xfc
	s_or_b32 s14, s14, s48
	s_mov_b32 s15, s49
	s_lshl_b64 s[14:15], s[14:15], 13
	v_lshl_add_u64 v[10:11], v[0:1], 0, s[14:15]
	global_store_dwordx2 v[10:11], v[32:33], off
	v_lshlrev_b32_e32 v8, 16, v44
	v_lshlrev_b32_e32 v19, 16, v46
	v_and_b32_e32 v29, 0xffff0000, v44
	v_and_b32_e32 v34, 0xffff0000, v46
	v_fma_f32 v20, -v18, v19, v8
	v_fma_f32 v21, -v18, v34, v29
	v_lshlrev_b32_e32 v8, 16, v45
	v_lshlrev_b32_e32 v19, 16, v47
	v_and_b32_e32 v29, 0xffff0000, v45
	v_and_b32_e32 v34, 0xffff0000, v47
	v_fma_f32 v30, -v18, v19, v8
	v_fma_f32 v31, -v18, v34, v29
	v_mul_f32_e32 v8, v21, v21
	v_mul_f32_e32 v19, v31, v31
	v_fmac_f32_e32 v8, v20, v20
	v_fmac_f32_e32 v19, v30, v30
	v_add_f32_e32 v8, v8, v19
	s_nop 1
	v_add_f32_dpp v8, v8, v8 quad_perm:[1,0,3,2] row_mask:0xf bank_mask:0xf
	s_nop 1
	v_add_f32_dpp v8, v8, v8 quad_perm:[2,3,0,1] row_mask:0xf bank_mask:0xf
	s_nop 1
	v_add_f32_dpp v8, v8, v8 row_half_mirror row_mask:0xf bank_mask:0xf
	s_nop 1
	v_add_f32_dpp v8, v8, v8 row_mirror row_mask:0xf bank_mask:0xf
	s_nop 1
	v_readlane_b32 s14, v8, 0
	v_readlane_b32 s15, v8, 16
	v_readlane_b32 s24, v8, 32
	v_readlane_b32 s25, v8, 48
	s_nop 2
	v_mov_b32_e32 v19, s15
	v_mov_b32_e32 v29, s25
	v_add_f32_e32 v19, s14, v19
	v_add_f32_e32 v29, s24, v29
	v_add_f32_e32 v8, v19, v29
	v_fmamk_f32 v8, v8, 0x3b800000, v191
	v_mul_f32_e32 v19, 0x4f800000, v8
	v_cmp_gt_f32_e32 vcc, s76, v8
	s_nop 1
	v_cndmask_b32_e32 v8, v8, v19, vcc
	v_sqrt_f32_e32 v19, v8
	s_nop 0
	v_add_u32_e32 v29, -1, v19
	v_add_u32_e32 v34, 1, v19
	v_fma_f32 v35, -v29, v19, v8
	v_fma_f32 v36, -v34, v19, v8
	v_cmp_ge_f32_e64 s[14:15], 0, v35
	s_nop 1
	v_cndmask_b32_e64 v19, v19, v29, s[14:15]
	v_cmp_lt_f32_e64 s[14:15], 0, v36
	s_nop 1
	v_cndmask_b32_e64 v19, v19, v34, s[14:15]
	v_mul_f32_e32 v29, 0x37800000, v19
	v_cndmask_b32_e32 v19, v19, v29, vcc
	v_cmp_class_f32_e32 vcc, v8, v192
	s_nop 1
	v_cndmask_b32_e32 v8, v19, v8, vcc
	v_div_scale_f32 v19, s[14:15], v8, v8, 1.0
	v_rcp_f32_e32 v34, v19
	v_div_scale_f32 v29, vcc, 1.0, v8, 1.0
	v_fma_f32 v35, -v19, v34, 1.0
	v_fmac_f32_e32 v34, v35, v34
	v_mul_f32_e32 v35, v29, v34
	v_fma_f32 v36, -v19, v35, v29
	v_fmac_f32_e32 v35, v36, v34
	v_fma_f32 v19, -v19, v35, v29
	v_div_fmas_f32 v19, v19, v34, v35
	v_div_fixup_f32 v8, v19, v8, 1.0
	v_mul_f32_e32 v20, v20, v8
	v_mul_f32_e32 v21, v21, v8
	v_mul_f32_e32 v30, v30, v8
	v_mul_f32_e32 v31, v31, v8
	v_mul_f32_e32 v20, v4, v20
	v_mul_f32_e32 v21, v5, v21
	v_mul_f32_e32 v30, v2, v30
	v_mul_f32_e32 v31, v3, v31
	v_cvt_pk_bf16_f32 v32, v20, v21
	v_cvt_pk_bf16_f32 v33, v30, v31
	s_add_u32 s14, s52, 0x2000
	s_addc_u32 s15, s53, 0
	global_store_dwordx2 v184, v[32:33], s[14:15]
	v_lshlrev_b32_e32 v8, 16, v48
	v_lshlrev_b32_e32 v19, 16, v50
	v_and_b32_e32 v29, 0xffff0000, v48
	v_and_b32_e32 v34, 0xffff0000, v50
	v_fma_f32 v20, -v18, v19, v8
	v_fma_f32 v21, -v18, v34, v29
	v_lshlrev_b32_e32 v8, 16, v49
	v_lshlrev_b32_e32 v19, 16, v51
	v_and_b32_e32 v29, 0xffff0000, v49
	v_and_b32_e32 v34, 0xffff0000, v51
	v_fma_f32 v30, -v18, v19, v8
	v_fma_f32 v31, -v18, v34, v29
	v_mul_f32_e32 v8, v21, v21
	v_mul_f32_e32 v19, v31, v31
	v_fmac_f32_e32 v8, v20, v20
	v_fmac_f32_e32 v19, v30, v30
	v_add_f32_e32 v8, v8, v19
	s_nop 1
	v_add_f32_dpp v8, v8, v8 quad_perm:[1,0,3,2] row_mask:0xf bank_mask:0xf
	s_nop 1
	v_add_f32_dpp v8, v8, v8 quad_perm:[2,3,0,1] row_mask:0xf bank_mask:0xf
	s_nop 1
	v_add_f32_dpp v8, v8, v8 row_half_mirror row_mask:0xf bank_mask:0xf
	s_nop 1
	v_add_f32_dpp v8, v8, v8 row_mirror row_mask:0xf bank_mask:0xf
	s_nop 1
	v_readlane_b32 s14, v8, 0
	v_readlane_b32 s15, v8, 16
	v_readlane_b32 s24, v8, 32
	v_readlane_b32 s25, v8, 48
	s_nop 2
	v_mov_b32_e32 v19, s15
	v_mov_b32_e32 v29, s25
	v_add_f32_e32 v19, s14, v19
	v_add_f32_e32 v29, s24, v29
	v_add_f32_e32 v8, v19, v29
	v_fmamk_f32 v8, v8, 0x3b800000, v191
	v_mul_f32_e32 v19, 0x4f800000, v8
	v_cmp_gt_f32_e32 vcc, s76, v8
	s_nop 1
	v_cndmask_b32_e32 v8, v8, v19, vcc
	v_sqrt_f32_e32 v19, v8
	s_nop 0
	v_add_u32_e32 v29, -1, v19
	v_add_u32_e32 v34, 1, v19
	v_fma_f32 v35, -v29, v19, v8
	v_fma_f32 v36, -v34, v19, v8
	v_cmp_ge_f32_e64 s[14:15], 0, v35
	s_nop 1
	v_cndmask_b32_e64 v19, v19, v29, s[14:15]
	v_cmp_lt_f32_e64 s[14:15], 0, v36
	s_nop 1
	v_cndmask_b32_e64 v19, v19, v34, s[14:15]
	v_mul_f32_e32 v29, 0x37800000, v19
	v_cndmask_b32_e32 v19, v19, v29, vcc
	v_cmp_class_f32_e32 vcc, v8, v192
	s_nop 1
	v_cndmask_b32_e32 v8, v19, v8, vcc
	v_div_scale_f32 v19, s[14:15], v8, v8, 1.0
	v_rcp_f32_e32 v34, v19
	v_div_scale_f32 v29, vcc, 1.0, v8, 1.0
	v_fma_f32 v35, -v19, v34, 1.0
	v_fmac_f32_e32 v34, v35, v34
	v_mul_f32_e32 v35, v29, v34
	v_fma_f32 v36, -v19, v35, v29
	v_fmac_f32_e32 v35, v36, v34
	v_fma_f32 v19, -v19, v35, v29
	v_div_fmas_f32 v19, v19, v34, v35
	v_div_fixup_f32 v8, v19, v8, 1.0
	v_mul_f32_e32 v20, v20, v8
	v_mul_f32_e32 v21, v21, v8
	v_mul_f32_e32 v30, v30, v8
	v_mul_f32_e32 v31, v31, v8
	v_mul_f32_e32 v20, v4, v20
	v_mul_f32_e32 v21, v5, v21
	v_mul_f32_e32 v30, v2, v30
	v_mul_f32_e32 v31, v3, v31
	v_cvt_pk_bf16_f32 v32, v20, v21
	v_cvt_pk_bf16_f32 v33, v30, v31
	s_lshl_b32 s14, s56, 3
	s_add_i32 s14, s14, s50
	s_add_i32 s14, s14, 2
	s_and_b32 s14, s14, 0xfe
	s_or_b32 s14, s14, s48
	s_mov_b32 s15, s49
	s_lshl_b64 s[14:15], s[14:15], 13
	v_lshl_add_u64 v[10:11], v[0:1], 0, s[14:15]
	global_store_dwordx2 v[10:11], v[32:33], off
	v_lshlrev_b32_e32 v8, 16, v52
	v_lshlrev_b32_e32 v19, 16, v54
	v_and_b32_e32 v29, 0xffff0000, v52
	v_and_b32_e32 v34, 0xffff0000, v54
	v_fma_f32 v20, -v18, v19, v8
	v_fma_f32 v21, -v18, v34, v29
	v_lshlrev_b32_e32 v8, 16, v53
	v_lshlrev_b32_e32 v19, 16, v55
	v_and_b32_e32 v29, 0xffff0000, v53
	v_and_b32_e32 v34, 0xffff0000, v55
	v_fma_f32 v30, -v18, v19, v8
	v_fma_f32 v31, -v18, v34, v29
	v_mul_f32_e32 v8, v21, v21
	v_mul_f32_e32 v19, v31, v31
	v_fmac_f32_e32 v8, v20, v20
	v_fmac_f32_e32 v19, v30, v30
	v_add_f32_e32 v8, v8, v19
	s_nop 1
	v_add_f32_dpp v8, v8, v8 quad_perm:[1,0,3,2] row_mask:0xf bank_mask:0xf
	s_nop 1
	v_add_f32_dpp v8, v8, v8 quad_perm:[2,3,0,1] row_mask:0xf bank_mask:0xf
	s_nop 1
	v_add_f32_dpp v8, v8, v8 row_half_mirror row_mask:0xf bank_mask:0xf
	s_nop 1
	v_add_f32_dpp v8, v8, v8 row_mirror row_mask:0xf bank_mask:0xf
	s_nop 1
	v_readlane_b32 s14, v8, 0
	v_readlane_b32 s15, v8, 16
	v_readlane_b32 s24, v8, 32
	v_readlane_b32 s25, v8, 48
	s_nop 2
	v_mov_b32_e32 v19, s15
	v_mov_b32_e32 v29, s25
	v_add_f32_e32 v19, s14, v19
	v_add_f32_e32 v29, s24, v29
	v_add_f32_e32 v8, v19, v29
	v_fmamk_f32 v8, v8, 0x3b800000, v191
	v_mul_f32_e32 v19, 0x4f800000, v8
	v_cmp_gt_f32_e32 vcc, s76, v8
	s_nop 1
	v_cndmask_b32_e32 v8, v8, v19, vcc
	v_sqrt_f32_e32 v19, v8
	s_nop 0
	v_add_u32_e32 v29, -1, v19
	v_add_u32_e32 v34, 1, v19
	v_fma_f32 v35, -v29, v19, v8
	v_fma_f32 v36, -v34, v19, v8
	v_cmp_ge_f32_e64 s[14:15], 0, v35
	s_nop 1
	v_cndmask_b32_e64 v19, v19, v29, s[14:15]
	v_cmp_lt_f32_e64 s[14:15], 0, v36
	s_nop 1
	v_cndmask_b32_e64 v19, v19, v34, s[14:15]
	v_mul_f32_e32 v29, 0x37800000, v19
	v_cndmask_b32_e32 v19, v19, v29, vcc
	v_cmp_class_f32_e32 vcc, v8, v192
	s_nop 1
	v_cndmask_b32_e32 v8, v19, v8, vcc
	v_div_scale_f32 v19, s[14:15], v8, v8, 1.0
	v_rcp_f32_e32 v34, v19
	v_div_scale_f32 v29, vcc, 1.0, v8, 1.0
	v_fma_f32 v35, -v19, v34, 1.0
	v_fmac_f32_e32 v34, v35, v34
	v_mul_f32_e32 v35, v29, v34
	v_fma_f32 v36, -v19, v35, v29
	v_fmac_f32_e32 v35, v36, v34
	v_fma_f32 v19, -v19, v35, v29
	v_div_fmas_f32 v19, v19, v34, v35
	v_div_fixup_f32 v8, v19, v8, 1.0
	v_mul_f32_e32 v20, v20, v8
	v_mul_f32_e32 v21, v21, v8
	v_mul_f32_e32 v30, v30, v8
	v_mul_f32_e32 v31, v31, v8
	v_mul_f32_e32 v20, v4, v20
	v_mul_f32_e32 v21, v5, v21
	v_mul_f32_e32 v30, v2, v30
	v_mul_f32_e32 v31, v3, v31
	v_cvt_pk_bf16_f32 v32, v20, v21
	v_cvt_pk_bf16_f32 v33, v30, v31
	s_add_u32 s14, s52, 0x6000
	s_addc_u32 s15, s53, 0
	global_store_dwordx2 v184, v[32:33], s[14:15]
	s_cmp_eq_u32 s56, 3
	s_cbranch_scc1 .Lcmb_last
	s_add_u32 s4, s96, 0x9000
	s_addc_u32 s5, s97, 0
	s_add_u32 s6, s98, 0x9000
	s_addc_u32 s7, s99, 0
	global_load_dwordx2 v[40:41], v184, s[4:5] offset:-4096
	global_load_dwordx2 v[42:43], v184, s[6:7] offset:-4096
	global_load_dwordx2 v[44:45], v184, s[4:5]
	global_load_dwordx2 v[46:47], v184, s[6:7]
	s_add_u32 s4, s4, 0x2000
	s_addc_u32 s5, s5, 0
	s_add_u32 s6, s6, 0x2000
	s_addc_u32 s7, s7, 0
	global_load_dwordx2 v[48:49], v184, s[4:5] offset:-4096
	global_load_dwordx2 v[50:51], v184, s[6:7] offset:-4096
	global_load_dwordx2 v[52:53], v184, s[4:5]
	global_load_dwordx2 v[54:55], v184, s[6:7]
	s_waitcnt vmcnt(12)
	s_branch .Lcmb_pb
.Lcmb_last:
	s_waitcnt vmcnt(4)
.Lcmb_pb:
	v_lshlrev_b32_e32 v8, 16, v56
	v_lshlrev_b32_e32 v19, 16, v58
	v_and_b32_e32 v29, 0xffff0000, v56
	v_and_b32_e32 v34, 0xffff0000, v58
	v_fma_f32 v20, -v18, v19, v8
	v_fma_f32 v21, -v18, v34, v29
	v_lshlrev_b32_e32 v8, 16, v57
	v_lshlrev_b32_e32 v19, 16, v59
	v_and_b32_e32 v29, 0xffff0000, v57
	v_and_b32_e32 v34, 0xffff0000, v59
	v_fma_f32 v30, -v18, v19, v8
	v_fma_f32 v31, -v18, v34, v29
	v_mul_f32_e32 v8, v21, v21
	v_mul_f32_e32 v19, v31, v31
	v_fmac_f32_e32 v8, v20, v20
	v_fmac_f32_e32 v19, v30, v30
	v_add_f32_e32 v8, v8, v19
	s_nop 1
	v_add_f32_dpp v8, v8, v8 quad_perm:[1,0,3,2] row_mask:0xf bank_mask:0xf
	s_nop 1
	v_add_f32_dpp v8, v8, v8 quad_perm:[2,3,0,1] row_mask:0xf bank_mask:0xf
	s_nop 1
	v_add_f32_dpp v8, v8, v8 row_half_mirror row_mask:0xf bank_mask:0xf
	s_nop 1
	v_add_f32_dpp v8, v8, v8 row_mirror row_mask:0xf bank_mask:0xf
	s_nop 1
	v_readlane_b32 s14, v8, 0
	v_readlane_b32 s15, v8, 16
	v_readlane_b32 s24, v8, 32
	v_readlane_b32 s25, v8, 48
	s_nop 2
	v_mov_b32_e32 v19, s15
	v_mov_b32_e32 v29, s25
	v_add_f32_e32 v19, s14, v19
	v_add_f32_e32 v29, s24, v29
	v_add_f32_e32 v8, v19, v29
	v_fmamk_f32 v8, v8, 0x3b800000, v191
	v_mul_f32_e32 v19, 0x4f800000, v8
	v_cmp_gt_f32_e32 vcc, s76, v8
	s_nop 1
	v_cndmask_b32_e32 v8, v8, v19, vcc
	v_sqrt_f32_e32 v19, v8
	s_nop 0
	v_add_u32_e32 v29, -1, v19
	v_add_u32_e32 v34, 1, v19
	v_fma_f32 v35, -v29, v19, v8
	v_fma_f32 v36, -v34, v19, v8
	v_cmp_ge_f32_e64 s[14:15], 0, v35
	s_nop 1
	v_cndmask_b32_e64 v19, v19, v29, s[14:15]
	v_cmp_lt_f32_e64 s[14:15], 0, v36
	s_nop 1
	v_cndmask_b32_e64 v19, v19, v34, s[14:15]
	v_mul_f32_e32 v29, 0x37800000, v19
	v_cndmask_b32_e32 v19, v19, v29, vcc
	v_cmp_class_f32_e32 vcc, v8, v192
	s_nop 1
	v_cndmask_b32_e32 v8, v19, v8, vcc
	v_div_scale_f32 v19, s[14:15], v8, v8, 1.0
	v_rcp_f32_e32 v34, v19
	v_div_scale_f32 v29, vcc, 1.0, v8, 1.0
	v_fma_f32 v35, -v19, v34, 1.0
	v_fmac_f32_e32 v34, v35, v34
	v_mul_f32_e32 v35, v29, v34
	v_fma_f32 v36, -v19, v35, v29
	v_fmac_f32_e32 v35, v36, v34
	v_fma_f32 v19, -v19, v35, v29
	v_div_fmas_f32 v19, v19, v34, v35
	v_div_fixup_f32 v8, v19, v8, 1.0
	v_mul_f32_e32 v20, v20, v8
	v_mul_f32_e32 v21, v21, v8
	v_mul_f32_e32 v30, v30, v8
	v_mul_f32_e32 v31, v31, v8
	v_mul_f32_e32 v20, v4, v20
	v_mul_f32_e32 v21, v5, v21
	v_mul_f32_e32 v30, v2, v30
	v_mul_f32_e32 v31, v3, v31
	v_cvt_pk_bf16_f32 v32, v20, v21
	v_cvt_pk_bf16_f32 v33, v30, v31
	s_lshl_b32 s14, s56, 3
	s_add_i32 s14, s14, s50
	s_add_i32 s14, s14, 4
	s_and_b32 s14, s14, 0xfc
	s_or_b32 s14, s14, s48
	s_mov_b32 s15, s49
	s_lshl_b64 s[14:15], s[14:15], 13
	v_lshl_add_u64 v[10:11], v[0:1], 0, s[14:15]
	global_store_dwordx2 v[10:11], v[32:33], off
	v_lshlrev_b32_e32 v8, 16, v60
	v_lshlrev_b32_e32 v19, 16, v62
	v_and_b32_e32 v29, 0xffff0000, v60
	v_and_b32_e32 v34, 0xffff0000, v62
	v_fma_f32 v20, -v18, v19, v8
	v_fma_f32 v21, -v18, v34, v29
	v_lshlrev_b32_e32 v8, 16, v61
	v_lshlrev_b32_e32 v19, 16, v63
	v_and_b32_e32 v29, 0xffff0000, v61
	v_and_b32_e32 v34, 0xffff0000, v63
	v_fma_f32 v30, -v18, v19, v8
	v_fma_f32 v31, -v18, v34, v29
	v_mul_f32_e32 v8, v21, v21
	v_mul_f32_e32 v19, v31, v31
	v_fmac_f32_e32 v8, v20, v20
	v_fmac_f32_e32 v19, v30, v30
	v_add_f32_e32 v8, v8, v19
	s_nop 1
	v_add_f32_dpp v8, v8, v8 quad_perm:[1,0,3,2] row_mask:0xf bank_mask:0xf
	s_nop 1
	v_add_f32_dpp v8, v8, v8 quad_perm:[2,3,0,1] row_mask:0xf bank_mask:0xf
	s_nop 1
	v_add_f32_dpp v8, v8, v8 row_half_mirror row_mask:0xf bank_mask:0xf
	s_nop 1
	v_add_f32_dpp v8, v8, v8 row_mirror row_mask:0xf bank_mask:0xf
	s_nop 1
	v_readlane_b32 s14, v8, 0
	v_readlane_b32 s15, v8, 16
	v_readlane_b32 s24, v8, 32
	v_readlane_b32 s25, v8, 48
	s_nop 2
	v_mov_b32_e32 v19, s15
	v_mov_b32_e32 v29, s25
	v_add_f32_e32 v19, s14, v19
	v_add_f32_e32 v29, s24, v29
	v_add_f32_e32 v8, v19, v29
	v_fmamk_f32 v8, v8, 0x3b800000, v191
	v_mul_f32_e32 v19, 0x4f800000, v8
	v_cmp_gt_f32_e32 vcc, s76, v8
	s_nop 1
	v_cndmask_b32_e32 v8, v8, v19, vcc
	v_sqrt_f32_e32 v19, v8
	s_nop 0
	v_add_u32_e32 v29, -1, v19
	v_add_u32_e32 v34, 1, v19
	v_fma_f32 v35, -v29, v19, v8
	v_fma_f32 v36, -v34, v19, v8
	v_cmp_ge_f32_e64 s[14:15], 0, v35
	s_nop 1
	v_cndmask_b32_e64 v19, v19, v29, s[14:15]
	v_cmp_lt_f32_e64 s[14:15], 0, v36
	s_nop 1
	v_cndmask_b32_e64 v19, v19, v34, s[14:15]
	v_mul_f32_e32 v29, 0x37800000, v19
	v_cndmask_b32_e32 v19, v19, v29, vcc
	v_cmp_class_f32_e32 vcc, v8, v192
	s_nop 1
	v_cndmask_b32_e32 v8, v19, v8, vcc
	v_div_scale_f32 v19, s[14:15], v8, v8, 1.0
	v_rcp_f32_e32 v34, v19
	v_div_scale_f32 v29, vcc, 1.0, v8, 1.0
	v_fma_f32 v35, -v19, v34, 1.0
	v_fmac_f32_e32 v34, v35, v34
	v_mul_f32_e32 v35, v29, v34
	v_fma_f32 v36, -v19, v35, v29
	v_fmac_f32_e32 v35, v36, v34
	v_fma_f32 v19, -v19, v35, v29
	v_div_fmas_f32 v19, v19, v34, v35
	v_div_fixup_f32 v8, v19, v8, 1.0
	v_mul_f32_e32 v20, v20, v8
	v_mul_f32_e32 v21, v21, v8
	v_mul_f32_e32 v30, v30, v8
	v_mul_f32_e32 v31, v31, v8
	v_mul_f32_e32 v20, v4, v20
	v_mul_f32_e32 v21, v5, v21
	v_mul_f32_e32 v30, v2, v30
	v_mul_f32_e32 v31, v3, v31
	v_cvt_pk_bf16_f32 v32, v20, v21
	v_cvt_pk_bf16_f32 v33, v30, v31
	s_add_u32 s14, s52, 0xa000
	s_addc_u32 s15, s53, 0
	global_store_dwordx2 v184, v[32:33], s[14:15]
	v_lshlrev_b32_e32 v8, 16, v64
	v_lshlrev_b32_e32 v19, 16, v66
	v_and_b32_e32 v29, 0xffff0000, v64
	v_and_b32_e32 v34, 0xffff0000, v66
	v_fma_f32 v20, -v18, v19, v8
	v_fma_f32 v21, -v18, v34, v29
	v_lshlrev_b32_e32 v8, 16, v65
	v_lshlrev_b32_e32 v19, 16, v67
	v_and_b32_e32 v29, 0xffff0000, v65
	v_and_b32_e32 v34, 0xffff0000, v67
	v_fma_f32 v30, -v18, v19, v8
	v_fma_f32 v31, -v18, v34, v29
	v_mul_f32_e32 v8, v21, v21
	v_mul_f32_e32 v19, v31, v31
	v_fmac_f32_e32 v8, v20, v20
	v_fmac_f32_e32 v19, v30, v30
	v_add_f32_e32 v8, v8, v19
	s_nop 1
	v_add_f32_dpp v8, v8, v8 quad_perm:[1,0,3,2] row_mask:0xf bank_mask:0xf
	s_nop 1
	v_add_f32_dpp v8, v8, v8 quad_perm:[2,3,0,1] row_mask:0xf bank_mask:0xf
	s_nop 1
	v_add_f32_dpp v8, v8, v8 row_half_mirror row_mask:0xf bank_mask:0xf
	s_nop 1
	v_add_f32_dpp v8, v8, v8 row_mirror row_mask:0xf bank_mask:0xf
	s_nop 1
	v_readlane_b32 s14, v8, 0
	v_readlane_b32 s15, v8, 16
	v_readlane_b32 s24, v8, 32
	v_readlane_b32 s25, v8, 48
	s_nop 2
	v_mov_b32_e32 v19, s15
	v_mov_b32_e32 v29, s25
	v_add_f32_e32 v19, s14, v19
	v_add_f32_e32 v29, s24, v29
	v_add_f32_e32 v8, v19, v29
	v_fmamk_f32 v8, v8, 0x3b800000, v191
	v_mul_f32_e32 v19, 0x4f800000, v8
	v_cmp_gt_f32_e32 vcc, s76, v8
	s_nop 1
	v_cndmask_b32_e32 v8, v8, v19, vcc
	v_sqrt_f32_e32 v19, v8
	s_nop 0
	v_add_u32_e32 v29, -1, v19
	v_add_u32_e32 v34, 1, v19
	v_fma_f32 v35, -v29, v19, v8
	v_fma_f32 v36, -v34, v19, v8
	v_cmp_ge_f32_e64 s[14:15], 0, v35
	s_nop 1
	v_cndmask_b32_e64 v19, v19, v29, s[14:15]
	v_cmp_lt_f32_e64 s[14:15], 0, v36
	s_nop 1
	v_cndmask_b32_e64 v19, v19, v34, s[14:15]
	v_mul_f32_e32 v29, 0x37800000, v19
	v_cndmask_b32_e32 v19, v19, v29, vcc
	v_cmp_class_f32_e32 vcc, v8, v192
	s_nop 1
	v_cndmask_b32_e32 v8, v19, v8, vcc
	v_div_scale_f32 v19, s[14:15], v8, v8, 1.0
	v_rcp_f32_e32 v34, v19
	v_div_scale_f32 v29, vcc, 1.0, v8, 1.0
	v_fma_f32 v35, -v19, v34, 1.0
	v_fmac_f32_e32 v34, v35, v34
	v_mul_f32_e32 v35, v29, v34
	v_fma_f32 v36, -v19, v35, v29
	v_fmac_f32_e32 v35, v36, v34
	v_fma_f32 v19, -v19, v35, v29
	v_div_fmas_f32 v19, v19, v34, v35
	v_div_fixup_f32 v8, v19, v8, 1.0
	v_mul_f32_e32 v20, v20, v8
	v_mul_f32_e32 v21, v21, v8
	v_mul_f32_e32 v30, v30, v8
	v_mul_f32_e32 v31, v31, v8
	v_mul_f32_e32 v20, v4, v20
	v_mul_f32_e32 v21, v5, v21
	v_mul_f32_e32 v30, v2, v30
	v_mul_f32_e32 v31, v3, v31
	v_cvt_pk_bf16_f32 v32, v20, v21
	v_cvt_pk_bf16_f32 v33, v30, v31
	s_lshl_b32 s14, s56, 3
	s_add_i32 s14, s14, s50
	s_add_i32 s14, s14, 6
	s_and_b32 s14, s14, 0xfe
	s_or_b32 s14, s14, s48
	s_mov_b32 s15, s49
	s_lshl_b64 s[14:15], s[14:15], 13
	v_lshl_add_u64 v[10:11], v[0:1], 0, s[14:15]
	global_store_dwordx2 v[10:11], v[32:33], off
	v_lshlrev_b32_e32 v8, 16, v68
	v_lshlrev_b32_e32 v19, 16, v70
	v_and_b32_e32 v29, 0xffff0000, v68
	v_and_b32_e32 v34, 0xffff0000, v70
	v_fma_f32 v20, -v18, v19, v8
	v_fma_f32 v21, -v18, v34, v29
	v_lshlrev_b32_e32 v8, 16, v69
	v_lshlrev_b32_e32 v19, 16, v71
	v_and_b32_e32 v29, 0xffff0000, v69
	v_and_b32_e32 v34, 0xffff0000, v71
	v_fma_f32 v30, -v18, v19, v8
	v_fma_f32 v31, -v18, v34, v29
	v_mul_f32_e32 v8, v21, v21
	v_mul_f32_e32 v19, v31, v31
	v_fmac_f32_e32 v8, v20, v20
	v_fmac_f32_e32 v19, v30, v30
	v_add_f32_e32 v8, v8, v19
	s_nop 1
	v_add_f32_dpp v8, v8, v8 quad_perm:[1,0,3,2] row_mask:0xf bank_mask:0xf
	s_nop 1
	v_add_f32_dpp v8, v8, v8 quad_perm:[2,3,0,1] row_mask:0xf bank_mask:0xf
	s_nop 1
	v_add_f32_dpp v8, v8, v8 row_half_mirror row_mask:0xf bank_mask:0xf
	s_nop 1
	v_add_f32_dpp v8, v8, v8 row_mirror row_mask:0xf bank_mask:0xf
	s_nop 1
	v_readlane_b32 s14, v8, 0
	v_readlane_b32 s15, v8, 16
	v_readlane_b32 s24, v8, 32
	v_readlane_b32 s25, v8, 48
	s_nop 2
	v_mov_b32_e32 v19, s15
	v_mov_b32_e32 v29, s25
	v_add_f32_e32 v19, s14, v19
	v_add_f32_e32 v29, s24, v29
	v_add_f32_e32 v8, v19, v29
	v_fmamk_f32 v8, v8, 0x3b800000, v191
	v_mul_f32_e32 v19, 0x4f800000, v8
	v_cmp_gt_f32_e32 vcc, s76, v8
	s_nop 1
	v_cndmask_b32_e32 v8, v8, v19, vcc
	v_sqrt_f32_e32 v19, v8
	s_nop 0
	v_add_u32_e32 v29, -1, v19
	v_add_u32_e32 v34, 1, v19
	v_fma_f32 v35, -v29, v19, v8
	v_fma_f32 v36, -v34, v19, v8
	v_cmp_ge_f32_e64 s[14:15], 0, v35
	s_nop 1
	v_cndmask_b32_e64 v19, v19, v29, s[14:15]
	v_cmp_lt_f32_e64 s[14:15], 0, v36
	s_nop 1
	v_cndmask_b32_e64 v19, v19, v34, s[14:15]
	v_mul_f32_e32 v29, 0x37800000, v19
	v_cndmask_b32_e32 v19, v19, v29, vcc
	v_cmp_class_f32_e32 vcc, v8, v192
	s_nop 1
	v_cndmask_b32_e32 v8, v19, v8, vcc
	v_div_scale_f32 v19, s[14:15], v8, v8, 1.0
	v_rcp_f32_e32 v34, v19
	v_div_scale_f32 v29, vcc, 1.0, v8, 1.0
	v_fma_f32 v35, -v19, v34, 1.0
	v_fmac_f32_e32 v34, v35, v34
	v_mul_f32_e32 v35, v29, v34
	v_fma_f32 v36, -v19, v35, v29
	v_fmac_f32_e32 v35, v36, v34
	v_fma_f32 v19, -v19, v35, v29
	v_div_fmas_f32 v19, v19, v34, v35
	v_div_fixup_f32 v8, v19, v8, 1.0
	v_mul_f32_e32 v20, v20, v8
	v_mul_f32_e32 v21, v21, v8
	v_mul_f32_e32 v30, v30, v8
	v_mul_f32_e32 v31, v31, v8
	v_mul_f32_e32 v20, v4, v20
	v_mul_f32_e32 v21, v5, v21
	v_mul_f32_e32 v30, v2, v30
	v_mul_f32_e32 v31, v3, v31
	v_cvt_pk_bf16_f32 v32, v20, v21
	v_cvt_pk_bf16_f32 v33, v30, v31
	s_add_u32 s14, s52, 0xe000
	s_addc_u32 s15, s53, 0
	global_store_dwordx2 v184, v[32:33], s[14:15]
	s_add_u32 s96, s96, 0x8000
	s_addc_u32 s97, s97, 0
	s_add_u32 s98, s98, 0x8000
	s_addc_u32 s99, s99, 0
	s_add_u32 s52, s52, 0x10000
	s_addc_u32 s53, s53, 0
	s_add_i32 s56, s56, 1
	s_cmp_eq_u32 s56, 4
	s_cbranch_scc0 .Lcmb_loop
	s_mov_b64 s[4:5], 0
	s_branch .LBB0_386
